# speedup vs baseline: 1.0311x; 1.0311x over previous
.LBB0_266:
	v_mov_b32_e32 v0, v190
	s_mov_b64 s[28:29], -1
	v_ashrrev_i32_e32 v131, 2, v0
	v_and_b32_e32 v130, 15, v0
	v_and_b32_e32 v131, 0xffffffc0, v131
	v_add3_u32 v198, v130, s60, v131
	v_lshrrev_b32_e32 v130, 1, v0
	v_and_b32_e32 v230, 0x60, v130
	v_lshrrev_b32_e32 v130, 2, v0
	v_and_b32_e32 v130, 12, v130
	v_and_b32_e32 v0, 16, v0
	v_add_u32_e32 v131, 12, v130
	v_cmp_eq_u32_e32 vcc, 0, v0
	v_add3_u32 v200, v230, s94, v130
	s_mov_b64 s[6:7], 0
	v_cndmask_b32_e32 v231, v131, v130, vcc
	s_cmp_lt_i32 s97, 1
	s_mov_b64 s[24:25], 0
	s_cbranch_scc1 .LBB0_282
	s_cmp_gt_i32 s97, 2
	s_cbranch_scc0 .LBB0_271
	s_cmp_eq_u32 s97, 3
	s_mov_b64 s[24:25], -1
	s_cbranch_scc0 .LBB0_270
	v_ashrrev_i32_e32 v199, 31, v198
	v_lshlrev_b64 v[130:131], 14, v[198:199]
	v_lshl_add_u64 v[130:131], s[34:35], 0, v[130:131]
	v_lshl_add_u64 v[130:131], s[94:95], 1, v[130:131]
	v_lshlrev_b32_e32 v0, 1, v230
	v_lshl_add_u64 v[130:131], v[130:131], 0, v[0:1]
	v_lshlrev_b32_e32 v0, 1, v231
	v_lshl_add_u64 v[130:131], v[130:131], 0, v[0:1]
	v_max_f32_e32 v0, 0, v126
	v_max_f32_e32 v132, 0, v127
	v_max_f32_e32 v133, 0, v128
	v_max_f32_e32 v134, 0, v129
	v_mul_f32_e32 v0, v0, v0
	v_mul_f32_e32 v132, v132, v132
	v_max_f32_e32 v135, 0, v122
	v_max_f32_e32 v136, 0, v123
	v_cvt_pk_bf16_f32 v132, v0, v132
	v_mul_f32_e32 v0, v133, v133
	v_mul_f32_e32 v133, v134, v134
	v_max_f32_e32 v137, 0, v124
	v_max_f32_e32 v138, 0, v125
	v_cvt_pk_bf16_f32 v133, v0, v133
	v_mul_f32_e32 v0, v135, v135
	v_mul_f32_e32 v134, v136, v136
	v_cvt_pk_bf16_f32 v134, v0, v134
	v_mul_f32_e32 v0, v137, v137
	v_mul_f32_e32 v135, v138, v138
	v_cvt_pk_bf16_f32 v135, v0, v135
	v_permlane16_swap_b32_e32 v132, v134
	s_nop 0
	v_permlane16_swap_b32_e32 v133, v135
	global_store_dwordx4 v[130:131], v[132:135], off
	s_nop 0
	v_max_f32_e32 v0, 0, v118
	v_max_f32_e32 v132, 0, v119
	v_max_f32_e32 v133, 0, v120
	v_max_f32_e32 v134, 0, v121
	v_mul_f32_e32 v0, v0, v0
	v_mul_f32_e32 v132, v132, v132
	v_max_f32_e32 v135, 0, v114
	v_max_f32_e32 v136, 0, v115
	v_cvt_pk_bf16_f32 v132, v0, v132
	v_mul_f32_e32 v0, v133, v133
	v_mul_f32_e32 v133, v134, v134
	v_max_f32_e32 v137, 0, v116
	v_max_f32_e32 v138, 0, v117
	v_cvt_pk_bf16_f32 v133, v0, v133
	v_mul_f32_e32 v0, v135, v135
	v_mul_f32_e32 v134, v136, v136
	v_cvt_pk_bf16_f32 v134, v0, v134
	v_mul_f32_e32 v0, v137, v137
	v_mul_f32_e32 v135, v138, v138
	v_cvt_pk_bf16_f32 v135, v0, v135
	v_add_co_u32_e32 v136, vcc, s12, v130
	v_permlane16_swap_b32_e32 v132, v134
	v_permlane16_swap_b32_e32 v133, v135
	v_addc_co_u32_e32 v137, vcc, 0, v131, vcc
	global_store_dwordx4 v[136:137], v[132:135], off
	s_nop 0
	v_max_f32_e32 v0, 0, v110
	v_max_f32_e32 v132, 0, v111
	v_max_f32_e32 v133, 0, v112
	v_max_f32_e32 v134, 0, v113
	v_mul_f32_e32 v0, v0, v0
	v_mul_f32_e32 v132, v132, v132
	v_max_f32_e32 v135, 0, v106
	v_max_f32_e32 v138, 0, v107
	v_cvt_pk_bf16_f32 v132, v0, v132
	v_mul_f32_e32 v0, v133, v133
	v_mul_f32_e32 v133, v134, v134
	v_max_f32_e32 v139, 0, v108
	v_max_f32_e32 v140, 0, v109
	v_cvt_pk_bf16_f32 v133, v0, v133
	v_mul_f32_e32 v0, v135, v135
	v_mul_f32_e32 v134, v138, v138
	v_cvt_pk_bf16_f32 v134, v0, v134
	v_mul_f32_e32 v0, v139, v139
	v_mul_f32_e32 v135, v140, v140
	s_mov_b32 s2, 0x80000
	v_cvt_pk_bf16_f32 v135, v0, v135
	v_add_co_u32_e32 v138, vcc, s2, v130
	v_permlane16_swap_b32_e32 v132, v134
	v_permlane16_swap_b32_e32 v133, v135
	v_addc_co_u32_e32 v139, vcc, 0, v131, vcc
	global_store_dwordx4 v[138:139], v[132:135], off
	s_nop 0
	v_max_f32_e32 v0, 0, v102
	v_max_f32_e32 v132, 0, v103
	v_max_f32_e32 v133, 0, v104
	v_max_f32_e32 v134, 0, v105
	v_mul_f32_e32 v0, v0, v0
	v_mul_f32_e32 v132, v132, v132
	v_max_f32_e32 v135, 0, v98
	v_max_f32_e32 v140, 0, v99
	v_cvt_pk_bf16_f32 v132, v0, v132
	v_mul_f32_e32 v0, v133, v133
	v_mul_f32_e32 v133, v134, v134
	v_max_f32_e32 v141, 0, v100
	v_max_f32_e32 v142, 0, v101
	v_cvt_pk_bf16_f32 v133, v0, v133
	v_mul_f32_e32 v0, v135, v135
	v_mul_f32_e32 v134, v140, v140
	v_cvt_pk_bf16_f32 v134, v0, v134
	v_mul_f32_e32 v0, v141, v141
	v_mul_f32_e32 v135, v142, v142
	s_mov_b32 s2, 0xc0000
	v_cvt_pk_bf16_f32 v135, v0, v135
	v_add_co_u32_e32 v140, vcc, s2, v130
	v_permlane16_swap_b32_e32 v132, v134
	v_permlane16_swap_b32_e32 v133, v135
	v_addc_co_u32_e32 v141, vcc, 0, v131, vcc
	global_store_dwordx4 v[140:141], v[132:135], off
	s_nop 0
	v_max_f32_e32 v0, 0, v94
	v_max_f32_e32 v132, 0, v95
	v_max_f32_e32 v133, 0, v96
	v_max_f32_e32 v134, 0, v97
	v_mul_f32_e32 v0, v0, v0
	v_mul_f32_e32 v132, v132, v132
	v_max_f32_e32 v135, 0, v90
	v_max_f32_e32 v142, 0, v91
	v_cvt_pk_bf16_f32 v132, v0, v132
	v_mul_f32_e32 v0, v133, v133
	v_mul_f32_e32 v133, v134, v134
	v_max_f32_e32 v143, 0, v92
	v_max_f32_e32 v144, 0, v93
	v_cvt_pk_bf16_f32 v133, v0, v133
	v_mul_f32_e32 v0, v135, v135
	v_mul_f32_e32 v134, v142, v142
	v_cvt_pk_bf16_f32 v134, v0, v134
	v_mul_f32_e32 v0, v143, v143
	v_mul_f32_e32 v135, v144, v144
	v_cvt_pk_bf16_f32 v135, v0, v135
	v_permlane16_swap_b32_e32 v132, v134
	s_nop 0
	v_permlane16_swap_b32_e32 v133, v135
	global_store_dwordx4 v[130:131], v[132:135], off offset:256
	s_nop 0
	v_max_f32_e32 v0, 0, v86
	v_max_f32_e32 v132, 0, v87
	v_max_f32_e32 v133, 0, v88
	v_max_f32_e32 v134, 0, v89
	v_mul_f32_e32 v0, v0, v0
	v_mul_f32_e32 v132, v132, v132
	v_max_f32_e32 v135, 0, v82
	v_max_f32_e32 v142, 0, v83
	v_cvt_pk_bf16_f32 v132, v0, v132
	v_mul_f32_e32 v0, v133, v133
	v_mul_f32_e32 v133, v134, v134
	v_max_f32_e32 v143, 0, v84
	v_max_f32_e32 v144, 0, v85
	v_cvt_pk_bf16_f32 v133, v0, v133
	v_mul_f32_e32 v0, v135, v135
	v_mul_f32_e32 v134, v142, v142
	v_cvt_pk_bf16_f32 v134, v0, v134
	v_mul_f32_e32 v0, v143, v143
	v_mul_f32_e32 v135, v144, v144
	v_cvt_pk_bf16_f32 v135, v0, v135
	v_permlane16_swap_b32_e32 v132, v134
	s_nop 0
	v_permlane16_swap_b32_e32 v133, v135
	global_store_dwordx4 v[136:137], v[132:135], off offset:256
	s_nop 0
	v_max_f32_e32 v0, 0, v78
	v_max_f32_e32 v132, 0, v79
	v_max_f32_e32 v133, 0, v80
	v_max_f32_e32 v134, 0, v81
	v_mul_f32_e32 v0, v0, v0
	v_mul_f32_e32 v132, v132, v132
	v_max_f32_e32 v135, 0, v74
	v_max_f32_e32 v136, 0, v75
	v_cvt_pk_bf16_f32 v132, v0, v132
	v_mul_f32_e32 v0, v133, v133
	v_mul_f32_e32 v133, v134, v134
	v_max_f32_e32 v137, 0, v76
	v_max_f32_e32 v142, 0, v77
	v_cvt_pk_bf16_f32 v133, v0, v133
	v_mul_f32_e32 v0, v135, v135
	v_mul_f32_e32 v134, v136, v136
	v_cvt_pk_bf16_f32 v134, v0, v134
	v_mul_f32_e32 v0, v137, v137
	v_mul_f32_e32 v135, v142, v142
	v_cvt_pk_bf16_f32 v135, v0, v135
	v_permlane16_swap_b32_e32 v132, v134
	s_nop 0
	v_permlane16_swap_b32_e32 v133, v135
	global_store_dwordx4 v[138:139], v[132:135], off offset:256
	s_nop 0
	v_max_f32_e32 v0, 0, v70
	v_max_f32_e32 v132, 0, v71
	v_max_f32_e32 v133, 0, v72
	v_max_f32_e32 v134, 0, v73
	v_mul_f32_e32 v0, v0, v0
	v_mul_f32_e32 v132, v132, v132
	v_max_f32_e32 v135, 0, v66
	v_max_f32_e32 v136, 0, v67
	v_cvt_pk_bf16_f32 v132, v0, v132
	v_mul_f32_e32 v0, v133, v133
	v_mul_f32_e32 v133, v134, v134
	v_max_f32_e32 v137, 0, v68
	v_max_f32_e32 v138, 0, v69
	v_cvt_pk_bf16_f32 v133, v0, v133
	v_mul_f32_e32 v0, v135, v135
	v_mul_f32_e32 v134, v136, v136
	v_cvt_pk_bf16_f32 v134, v0, v134
	v_mul_f32_e32 v0, v137, v137
	v_mul_f32_e32 v135, v138, v138
	v_cvt_pk_bf16_f32 v135, v0, v135
	v_permlane16_swap_b32_e32 v132, v134
	s_nop 0
	v_permlane16_swap_b32_e32 v133, v135
	global_store_dwordx4 v[140:141], v[132:135], off offset:256
	s_nop 0
	v_max_f32_e32 v0, 0, v62
	v_max_f32_e32 v132, 0, v63
	v_max_f32_e32 v133, 0, v64
	v_max_f32_e32 v134, 0, v65
	v_mul_f32_e32 v0, v0, v0
	v_mul_f32_e32 v132, v132, v132
	v_max_f32_e32 v135, 0, v58
	v_max_f32_e32 v136, 0, v59
	v_cvt_pk_bf16_f32 v132, v0, v132
	v_mul_f32_e32 v0, v133, v133
	v_mul_f32_e32 v133, v134, v134
	v_max_f32_e32 v137, 0, v60
	v_max_f32_e32 v138, 0, v61
	v_cvt_pk_bf16_f32 v133, v0, v133
	v_mul_f32_e32 v0, v135, v135
	v_mul_f32_e32 v134, v136, v136
	v_cvt_pk_bf16_f32 v134, v0, v134
	v_mul_f32_e32 v0, v137, v137
	v_mul_f32_e32 v135, v138, v138
	s_mov_b32 s2, 0x200000
	v_cvt_pk_bf16_f32 v135, v0, v135
	v_add_co_u32_e32 v136, vcc, s2, v130
	v_permlane16_swap_b32_e32 v132, v134
	v_permlane16_swap_b32_e32 v133, v135
	v_addc_co_u32_e32 v137, vcc, 0, v131, vcc
	global_store_dwordx4 v[136:137], v[132:135], off
	s_nop 0
	v_max_f32_e32 v0, 0, v54
	v_max_f32_e32 v132, 0, v55
	v_max_f32_e32 v133, 0, v56
	v_max_f32_e32 v134, 0, v57
	v_mul_f32_e32 v0, v0, v0
	v_mul_f32_e32 v132, v132, v132
	v_max_f32_e32 v135, 0, v50
	v_max_f32_e32 v138, 0, v51
	v_cvt_pk_bf16_f32 v132, v0, v132
	v_mul_f32_e32 v0, v133, v133
	v_mul_f32_e32 v133, v134, v134
	v_max_f32_e32 v139, 0, v52
	v_max_f32_e32 v140, 0, v53
	v_cvt_pk_bf16_f32 v133, v0, v133
	v_mul_f32_e32 v0, v135, v135
	v_mul_f32_e32 v134, v138, v138
	v_cvt_pk_bf16_f32 v134, v0, v134
	v_mul_f32_e32 v0, v139, v139
	v_mul_f32_e32 v135, v140, v140
	s_mov_b32 s2, 0x240000
	v_cvt_pk_bf16_f32 v135, v0, v135
	v_add_co_u32_e32 v138, vcc, s2, v130
	v_permlane16_swap_b32_e32 v132, v134
	v_permlane16_swap_b32_e32 v133, v135
	v_addc_co_u32_e32 v139, vcc, 0, v131, vcc
	global_store_dwordx4 v[138:139], v[132:135], off
	s_nop 0
	v_max_f32_e32 v0, 0, v46
	v_max_f32_e32 v132, 0, v47
	v_max_f32_e32 v133, 0, v48
	v_max_f32_e32 v134, 0, v49
	v_mul_f32_e32 v0, v0, v0
	v_mul_f32_e32 v132, v132, v132
	v_max_f32_e32 v135, 0, v42
	v_max_f32_e32 v140, 0, v43
	v_cvt_pk_bf16_f32 v132, v0, v132
	v_mul_f32_e32 v0, v133, v133
	v_mul_f32_e32 v133, v134, v134
	v_max_f32_e32 v141, 0, v44
	v_max_f32_e32 v142, 0, v45
	v_cvt_pk_bf16_f32 v133, v0, v133
	v_mul_f32_e32 v0, v135, v135
	v_mul_f32_e32 v134, v140, v140
	v_cvt_pk_bf16_f32 v134, v0, v134
	v_mul_f32_e32 v0, v141, v141
	v_mul_f32_e32 v135, v142, v142
	s_mov_b32 s2, 0x280000
	v_cvt_pk_bf16_f32 v135, v0, v135
	v_add_co_u32_e32 v140, vcc, s2, v130
	v_permlane16_swap_b32_e32 v132, v134
	v_permlane16_swap_b32_e32 v133, v135
	v_addc_co_u32_e32 v141, vcc, 0, v131, vcc
	global_store_dwordx4 v[140:141], v[132:135], off
	s_nop 0
	v_max_f32_e32 v0, 0, v38
	v_max_f32_e32 v132, 0, v39
	v_max_f32_e32 v133, 0, v40
	v_max_f32_e32 v134, 0, v41
	v_mul_f32_e32 v0, v0, v0
	v_mul_f32_e32 v132, v132, v132
	v_max_f32_e32 v135, 0, v34
	v_max_f32_e32 v142, 0, v35
	v_cvt_pk_bf16_f32 v132, v0, v132
	v_mul_f32_e32 v0, v133, v133
	v_mul_f32_e32 v133, v134, v134
	v_max_f32_e32 v143, 0, v36
	v_max_f32_e32 v144, 0, v37
	v_cvt_pk_bf16_f32 v133, v0, v133
	v_mul_f32_e32 v0, v135, v135
	v_mul_f32_e32 v134, v142, v142
	v_cvt_pk_bf16_f32 v134, v0, v134
	v_mul_f32_e32 v0, v143, v143
	v_mul_f32_e32 v135, v144, v144
	s_mov_b32 s2, 0x2c0000
	v_cvt_pk_bf16_f32 v135, v0, v135
	v_add_co_u32_e32 v142, vcc, s2, v130
	v_permlane16_swap_b32_e32 v132, v134
	v_permlane16_swap_b32_e32 v133, v135
	v_addc_co_u32_e32 v143, vcc, 0, v131, vcc
	global_store_dwordx4 v[142:143], v[132:135], off
	v_max_f32_e32 v0, 0, v30
	v_max_f32_e32 v130, 0, v31
	v_max_f32_e32 v131, 0, v32
	v_max_f32_e32 v132, 0, v33
	v_mul_f32_e32 v0, v0, v0
	v_mul_f32_e32 v130, v130, v130
	v_max_f32_e32 v133, 0, v26
	v_max_f32_e32 v134, 0, v27
	v_cvt_pk_bf16_f32 v130, v0, v130
	v_mul_f32_e32 v0, v131, v131
	v_mul_f32_e32 v131, v132, v132
	v_max_f32_e32 v135, 0, v28
	v_max_f32_e32 v144, 0, v29
	v_cvt_pk_bf16_f32 v131, v0, v131
	v_mul_f32_e32 v0, v133, v133
	v_mul_f32_e32 v132, v134, v134
	v_cvt_pk_bf16_f32 v132, v0, v132
	v_mul_f32_e32 v0, v135, v135
	v_mul_f32_e32 v133, v144, v144
	v_cvt_pk_bf16_f32 v133, v0, v133
	v_permlane16_swap_b32_e32 v130, v132
	s_nop 0
	v_permlane16_swap_b32_e32 v131, v133
	global_store_dwordx4 v[136:137], v[130:133], off offset:256
	s_nop 0
	v_max_f32_e32 v0, 0, v22
	v_max_f32_e32 v130, 0, v23
	v_max_f32_e32 v131, 0, v24
	v_max_f32_e32 v132, 0, v25
	v_mul_f32_e32 v0, v0, v0
	v_mul_f32_e32 v130, v130, v130
	v_max_f32_e32 v133, 0, v18
	v_max_f32_e32 v134, 0, v19
	v_cvt_pk_bf16_f32 v130, v0, v130
	v_mul_f32_e32 v0, v131, v131
	v_mul_f32_e32 v131, v132, v132
	v_max_f32_e32 v135, 0, v20
	v_max_f32_e32 v136, 0, v21
	v_cvt_pk_bf16_f32 v131, v0, v131
	v_mul_f32_e32 v0, v133, v133
	v_mul_f32_e32 v132, v134, v134
	v_cvt_pk_bf16_f32 v132, v0, v132
	v_mul_f32_e32 v0, v135, v135
	v_mul_f32_e32 v133, v136, v136
	v_cvt_pk_bf16_f32 v133, v0, v133
	v_permlane16_swap_b32_e32 v130, v132
	s_nop 0
	v_permlane16_swap_b32_e32 v131, v133
	global_store_dwordx4 v[138:139], v[130:133], off offset:256
	s_nop 0
	v_max_f32_e32 v0, 0, v14
	v_max_f32_e32 v130, 0, v15
	v_max_f32_e32 v131, 0, v16
	v_max_f32_e32 v132, 0, v17
	v_mul_f32_e32 v0, v0, v0
	v_mul_f32_e32 v130, v130, v130
	v_max_f32_e32 v133, 0, v10
	v_max_f32_e32 v134, 0, v11
	v_cvt_pk_bf16_f32 v130, v0, v130
	v_mul_f32_e32 v0, v131, v131
	v_mul_f32_e32 v131, v132, v132
	v_max_f32_e32 v135, 0, v12
	v_max_f32_e32 v136, 0, v13
	v_cvt_pk_bf16_f32 v131, v0, v131
	v_mul_f32_e32 v0, v133, v133
	v_mul_f32_e32 v132, v134, v134
	v_cvt_pk_bf16_f32 v132, v0, v132
	v_mul_f32_e32 v0, v135, v135
	v_mul_f32_e32 v133, v136, v136
	v_cvt_pk_bf16_f32 v133, v0, v133
	v_permlane16_swap_b32_e32 v130, v132
	s_nop 0
	v_permlane16_swap_b32_e32 v131, v133
	global_store_dwordx4 v[140:141], v[130:133], off offset:256
	s_nop 0
	v_max_f32_e32 v0, 0, v6
	v_max_f32_e32 v130, 0, v7
	v_max_f32_e32 v131, 0, v8
	v_max_f32_e32 v132, 0, v9
	v_mul_f32_e32 v0, v0, v0
	v_mul_f32_e32 v130, v130, v130
	v_max_f32_e32 v133, 0, v2
	v_max_f32_e32 v134, 0, v3
	v_cvt_pk_bf16_f32 v130, v0, v130
	v_mul_f32_e32 v0, v131, v131
	v_mul_f32_e32 v131, v132, v132
	v_max_f32_e32 v135, 0, v4
	v_max_f32_e32 v136, 0, v5
	v_cvt_pk_bf16_f32 v131, v0, v131
	v_mul_f32_e32 v0, v133, v133
	v_mul_f32_e32 v132, v134, v134
	v_cvt_pk_bf16_f32 v132, v0, v132
	v_mul_f32_e32 v0, v135, v135
	v_mul_f32_e32 v133, v136, v136
	v_cvt_pk_bf16_f32 v133, v0, v133
	v_permlane16_swap_b32_e32 v130, v132
	s_nop 0
	v_permlane16_swap_b32_e32 v131, v133
	global_store_dwordx4 v[142:143], v[130:133], off offset:256
	s_mov_b64 s[24:25], 0
